# GLU epilogue hand-written: all sigmoids run behind the eight gate loads, then one wait and the gate multiplies and stores
# speedup vs baseline: 1.0011x; 1.0011x over previous
.LBB0_616:
	v_lshl_add_u32 v146, s20, 8, v148
	v_lshl_or_b32 v144, s21, 7, v150
	v_ashrrev_i32_e32 v147, 31, v146
	v_ashrrev_i32_e32 v145, 31, v144
	v_lshlrev_b64 v[154:155], 13, v[146:147]
	v_lshl_add_u64 v[154:155], s[8:9], 0, v[154:155]
	v_lshlrev_b64 v[144:145], 1, v[144:145]
	v_lshl_add_u64 v[154:155], v[154:155], 0, v[144:145]
	v_add_co_u32_e32 v216, vcc, 0x20000, v154
	v_addc_co_u32_e32 v217, vcc, 0, v155, vcc
	global_load_dwordx4 v[220:223], v[216:217], off
	v_add_co_u32_e32 v216, vcc, 0x40000, v154
	v_addc_co_u32_e32 v217, vcc, 0, v155, vcc
	global_load_dwordx4 v[224:227], v[216:217], off
	v_add_co_u32_e32 v216, vcc, 0x60000, v154
	v_addc_co_u32_e32 v217, vcc, 0, v155, vcc
	global_load_dwordx4 v[228:231], v[216:217], off
	v_add_co_u32_e32 v216, vcc, 0x100000, v154
	v_addc_co_u32_e32 v217, vcc, 0, v155, vcc
	global_load_dwordx4 v[232:235], v[216:217], off
	v_add_co_u32_e32 v216, vcc, 0x120000, v154
	v_addc_co_u32_e32 v217, vcc, 0, v155, vcc
	global_load_dwordx4 v[236:239], v[216:217], off
	v_add_co_u32_e32 v216, vcc, 0x140000, v154
	v_addc_co_u32_e32 v217, vcc, 0, v155, vcc
	global_load_dwordx4 v[240:243], v[216:217], off
	v_add_co_u32_e32 v216, vcc, 0x160000, v154
	v_addc_co_u32_e32 v217, vcc, 0, v155, vcc
	global_load_dwordx4 v[244:247], v[216:217], off
	global_load_dwordx4 v[154:157], v[154:155], off
	v_mul_f32_e32 v116, 0xbfb8aa3b, v116
	v_mul_f32_e32 v117, 0xbfb8aa3b, v117
	v_mul_f32_e32 v118, 0xbfb8aa3b, v118
	v_mul_f32_e32 v119, 0xbfb8aa3b, v119
	v_mul_f32_e32 v112, 0xbfb8aa3b, v112
	v_mul_f32_e32 v113, 0xbfb8aa3b, v113
	v_mul_f32_e32 v114, 0xbfb8aa3b, v114
	v_mul_f32_e32 v115, 0xbfb8aa3b, v115
	v_exp_f32_e32 v116, v116
	v_exp_f32_e32 v117, v117
	v_exp_f32_e32 v118, v118
	v_exp_f32_e32 v119, v119
	v_exp_f32_e32 v112, v112
	v_exp_f32_e32 v113, v113
	v_exp_f32_e32 v114, v114
	v_exp_f32_e32 v115, v115
	v_add_f32_e32 v116, 1.0, v116
	v_add_f32_e32 v117, 1.0, v117
	v_add_f32_e32 v118, 1.0, v118
	v_add_f32_e32 v119, 1.0, v119
	v_add_f32_e32 v112, 1.0, v112
	v_add_f32_e32 v113, 1.0, v113
	v_add_f32_e32 v114, 1.0, v114
	v_add_f32_e32 v115, 1.0, v115
	v_rcp_f32_e32 v116, v116
	v_rcp_f32_e32 v117, v117
	v_rcp_f32_e32 v118, v118
	v_rcp_f32_e32 v119, v119
	v_rcp_f32_e32 v112, v112
	v_rcp_f32_e32 v113, v113
	v_rcp_f32_e32 v114, v114
	v_rcp_f32_e32 v115, v115
	v_mul_f32_e32 v100, 0xbfb8aa3b, v100
	v_mul_f32_e32 v101, 0xbfb8aa3b, v101
	v_mul_f32_e32 v102, 0xbfb8aa3b, v102
	v_mul_f32_e32 v103, 0xbfb8aa3b, v103
	v_mul_f32_e32 v96, 0xbfb8aa3b, v96
	v_mul_f32_e32 v97, 0xbfb8aa3b, v97
	v_mul_f32_e32 v98, 0xbfb8aa3b, v98
	v_mul_f32_e32 v99, 0xbfb8aa3b, v99
	v_exp_f32_e32 v100, v100
	v_exp_f32_e32 v101, v101
	v_exp_f32_e32 v102, v102
	v_exp_f32_e32 v103, v103
	v_exp_f32_e32 v96, v96
	v_exp_f32_e32 v97, v97
	v_exp_f32_e32 v98, v98
	v_exp_f32_e32 v99, v99
	v_add_f32_e32 v100, 1.0, v100
	v_add_f32_e32 v101, 1.0, v101
	v_add_f32_e32 v102, 1.0, v102
	v_add_f32_e32 v103, 1.0, v103
	v_add_f32_e32 v96, 1.0, v96
	v_add_f32_e32 v97, 1.0, v97
	v_add_f32_e32 v98, 1.0, v98
	v_add_f32_e32 v99, 1.0, v99
	v_rcp_f32_e32 v100, v100
	v_rcp_f32_e32 v101, v101
	v_rcp_f32_e32 v102, v102
	v_rcp_f32_e32 v103, v103
	v_rcp_f32_e32 v96, v96
	v_rcp_f32_e32 v97, v97
	v_rcp_f32_e32 v98, v98
	v_rcp_f32_e32 v99, v99
	v_mul_f32_e32 v84, 0xbfb8aa3b, v84
	v_mul_f32_e32 v85, 0xbfb8aa3b, v85
	v_mul_f32_e32 v86, 0xbfb8aa3b, v86
	v_mul_f32_e32 v87, 0xbfb8aa3b, v87
	v_mul_f32_e32 v80, 0xbfb8aa3b, v80
	v_mul_f32_e32 v81, 0xbfb8aa3b, v81
	v_mul_f32_e32 v82, 0xbfb8aa3b, v82
	v_mul_f32_e32 v83, 0xbfb8aa3b, v83
	v_exp_f32_e32 v84, v84
	v_exp_f32_e32 v85, v85
	v_exp_f32_e32 v86, v86
	v_exp_f32_e32 v87, v87
	v_exp_f32_e32 v80, v80
	v_exp_f32_e32 v81, v81
	v_exp_f32_e32 v82, v82
	v_exp_f32_e32 v83, v83
	v_add_f32_e32 v84, 1.0, v84
	v_add_f32_e32 v85, 1.0, v85
	v_add_f32_e32 v86, 1.0, v86
	v_add_f32_e32 v87, 1.0, v87
	v_add_f32_e32 v80, 1.0, v80
	v_add_f32_e32 v81, 1.0, v81
	v_add_f32_e32 v82, 1.0, v82
	v_add_f32_e32 v83, 1.0, v83
	v_rcp_f32_e32 v84, v84
	v_rcp_f32_e32 v85, v85
	v_rcp_f32_e32 v86, v86
	v_rcp_f32_e32 v87, v87
	v_rcp_f32_e32 v80, v80
	v_rcp_f32_e32 v81, v81
	v_rcp_f32_e32 v82, v82
	v_rcp_f32_e32 v83, v83
	v_mul_f32_e32 v68, 0xbfb8aa3b, v68
	v_mul_f32_e32 v69, 0xbfb8aa3b, v69
	v_mul_f32_e32 v70, 0xbfb8aa3b, v70
	v_mul_f32_e32 v71, 0xbfb8aa3b, v71
	v_mul_f32_e32 v64, 0xbfb8aa3b, v64
	v_mul_f32_e32 v65, 0xbfb8aa3b, v65
	v_mul_f32_e32 v66, 0xbfb8aa3b, v66
	v_mul_f32_e32 v67, 0xbfb8aa3b, v67
	v_exp_f32_e32 v68, v68
	v_exp_f32_e32 v69, v69
	v_exp_f32_e32 v70, v70
	v_exp_f32_e32 v71, v71
	v_exp_f32_e32 v64, v64
	v_exp_f32_e32 v65, v65
	v_exp_f32_e32 v66, v66
	v_exp_f32_e32 v67, v67
	v_add_f32_e32 v68, 1.0, v68
	v_add_f32_e32 v69, 1.0, v69
	v_add_f32_e32 v70, 1.0, v70
	v_add_f32_e32 v71, 1.0, v71
	v_add_f32_e32 v64, 1.0, v64
	v_add_f32_e32 v65, 1.0, v65
	v_add_f32_e32 v66, 1.0, v66
	v_add_f32_e32 v67, 1.0, v67
	v_rcp_f32_e32 v68, v68
	v_rcp_f32_e32 v69, v69
	v_rcp_f32_e32 v70, v70
	v_rcp_f32_e32 v71, v71
	v_rcp_f32_e32 v64, v64
	v_rcp_f32_e32 v65, v65
	v_rcp_f32_e32 v66, v66
	v_rcp_f32_e32 v67, v67
	v_mul_f32_e32 v52, 0xbfb8aa3b, v52
	v_mul_f32_e32 v53, 0xbfb8aa3b, v53
	v_mul_f32_e32 v54, 0xbfb8aa3b, v54
	v_mul_f32_e32 v55, 0xbfb8aa3b, v55
	v_mul_f32_e32 v48, 0xbfb8aa3b, v48
	v_mul_f32_e32 v49, 0xbfb8aa3b, v49
	v_mul_f32_e32 v50, 0xbfb8aa3b, v50
	v_mul_f32_e32 v51, 0xbfb8aa3b, v51
	v_exp_f32_e32 v52, v52
	v_exp_f32_e32 v53, v53
	v_exp_f32_e32 v54, v54
	v_exp_f32_e32 v55, v55
	v_exp_f32_e32 v48, v48
	v_exp_f32_e32 v49, v49
	v_exp_f32_e32 v50, v50
	v_exp_f32_e32 v51, v51
	v_add_f32_e32 v52, 1.0, v52
	v_add_f32_e32 v53, 1.0, v53
	v_add_f32_e32 v54, 1.0, v54
	v_add_f32_e32 v55, 1.0, v55
	v_add_f32_e32 v48, 1.0, v48
	v_add_f32_e32 v49, 1.0, v49
	v_add_f32_e32 v50, 1.0, v50
	v_add_f32_e32 v51, 1.0, v51
	v_rcp_f32_e32 v52, v52
	v_rcp_f32_e32 v53, v53
	v_rcp_f32_e32 v54, v54
	v_rcp_f32_e32 v55, v55
	v_rcp_f32_e32 v48, v48
	v_rcp_f32_e32 v49, v49
	v_rcp_f32_e32 v50, v50
	v_rcp_f32_e32 v51, v51
	v_mul_f32_e32 v36, 0xbfb8aa3b, v36
	v_mul_f32_e32 v37, 0xbfb8aa3b, v37
	v_mul_f32_e32 v38, 0xbfb8aa3b, v38
	v_mul_f32_e32 v39, 0xbfb8aa3b, v39
	v_mul_f32_e32 v32, 0xbfb8aa3b, v32
	v_mul_f32_e32 v33, 0xbfb8aa3b, v33
	v_mul_f32_e32 v34, 0xbfb8aa3b, v34
	v_mul_f32_e32 v35, 0xbfb8aa3b, v35
	v_exp_f32_e32 v36, v36
	v_exp_f32_e32 v37, v37
	v_exp_f32_e32 v38, v38
	v_exp_f32_e32 v39, v39
	v_exp_f32_e32 v32, v32
	v_exp_f32_e32 v33, v33
	v_exp_f32_e32 v34, v34
	v_exp_f32_e32 v35, v35
	v_add_f32_e32 v36, 1.0, v36
	v_add_f32_e32 v37, 1.0, v37
	v_add_f32_e32 v38, 1.0, v38
	v_add_f32_e32 v39, 1.0, v39
	v_add_f32_e32 v32, 1.0, v32
	v_add_f32_e32 v33, 1.0, v33
	v_add_f32_e32 v34, 1.0, v34
	v_add_f32_e32 v35, 1.0, v35
	v_rcp_f32_e32 v36, v36
	v_rcp_f32_e32 v37, v37
	v_rcp_f32_e32 v38, v38
	v_rcp_f32_e32 v39, v39
	v_rcp_f32_e32 v32, v32
	v_rcp_f32_e32 v33, v33
	v_rcp_f32_e32 v34, v34
	v_rcp_f32_e32 v35, v35
	v_mul_f32_e32 v20, 0xbfb8aa3b, v20
	v_mul_f32_e32 v21, 0xbfb8aa3b, v21
	v_mul_f32_e32 v22, 0xbfb8aa3b, v22
	v_mul_f32_e32 v23, 0xbfb8aa3b, v23
	v_mul_f32_e32 v16, 0xbfb8aa3b, v16
	v_mul_f32_e32 v17, 0xbfb8aa3b, v17
	v_mul_f32_e32 v18, 0xbfb8aa3b, v18
	v_mul_f32_e32 v19, 0xbfb8aa3b, v19
	v_exp_f32_e32 v20, v20
	v_exp_f32_e32 v21, v21
	v_exp_f32_e32 v22, v22
	v_exp_f32_e32 v23, v23
	v_exp_f32_e32 v16, v16
	v_exp_f32_e32 v17, v17
	v_exp_f32_e32 v18, v18
	v_exp_f32_e32 v19, v19
	v_add_f32_e32 v20, 1.0, v20
	v_add_f32_e32 v21, 1.0, v21
	v_add_f32_e32 v22, 1.0, v22
	v_add_f32_e32 v23, 1.0, v23
	v_add_f32_e32 v16, 1.0, v16
	v_add_f32_e32 v17, 1.0, v17
	v_add_f32_e32 v18, 1.0, v18
	v_add_f32_e32 v19, 1.0, v19
	v_rcp_f32_e32 v20, v20
	v_rcp_f32_e32 v21, v21
	v_rcp_f32_e32 v22, v22
	v_rcp_f32_e32 v23, v23
	v_rcp_f32_e32 v16, v16
	v_rcp_f32_e32 v17, v17
	v_rcp_f32_e32 v18, v18
	v_rcp_f32_e32 v19, v19
	v_mul_f32_e32 v4, 0xbfb8aa3b, v4
	v_mul_f32_e32 v5, 0xbfb8aa3b, v5
	v_mul_f32_e32 v6, 0xbfb8aa3b, v6
	v_mul_f32_e32 v7, 0xbfb8aa3b, v7
	v_mul_f32_e32 v0, 0xbfb8aa3b, v0
	v_mul_f32_e32 v1, 0xbfb8aa3b, v1
	v_mul_f32_e32 v2, 0xbfb8aa3b, v2
	v_mul_f32_e32 v3, 0xbfb8aa3b, v3
	v_exp_f32_e32 v4, v4
	v_exp_f32_e32 v5, v5
	v_exp_f32_e32 v6, v6
	v_exp_f32_e32 v7, v7
	v_exp_f32_e32 v0, v0
	v_exp_f32_e32 v1, v1
	v_exp_f32_e32 v2, v2
	v_exp_f32_e32 v3, v3
	v_add_f32_e32 v4, 1.0, v4
	v_add_f32_e32 v5, 1.0, v5
	v_add_f32_e32 v6, 1.0, v6
	v_add_f32_e32 v7, 1.0, v7
	v_add_f32_e32 v0, 1.0, v0
	v_add_f32_e32 v1, 1.0, v1
	v_add_f32_e32 v2, 1.0, v2
	v_add_f32_e32 v3, 1.0, v3
	v_rcp_f32_e32 v4, v4
	v_rcp_f32_e32 v5, v5
	v_rcp_f32_e32 v6, v6
	v_rcp_f32_e32 v7, v7
	v_rcp_f32_e32 v0, v0
	v_rcp_f32_e32 v1, v1
	v_rcp_f32_e32 v2, v2
	v_rcp_f32_e32 v3, v3
	v_lshl_add_u32 v147, v146, 12, v144
	s_waitcnt vmcnt(0)
	v_lshlrev_b32_e32 v158, 16, v154
	v_and_b32_e32 v159, 0xffff0000, v154
	v_lshlrev_b32_e32 v160, 16, v155
	v_and_b32_e32 v161, 0xffff0000, v155
	v_lshlrev_b32_e32 v216, 16, v156
	v_and_b32_e32 v217, 0xffff0000, v156
	v_lshlrev_b32_e32 v218, 16, v157
	v_and_b32_e32 v219, 0xffff0000, v157
	v_pk_mul_f32 v[124:125], v[124:125], v[158:159]
	v_pk_mul_f32 v[126:127], v[126:127], v[160:161]
	v_pk_mul_f32 v[120:121], v[120:121], v[216:217]
	v_pk_mul_f32 v[122:123], v[122:123], v[218:219]
	v_pk_mul_f32 v[116:117], v[116:117], v[124:125]
	v_pk_mul_f32 v[118:119], v[118:119], v[126:127]
	v_pk_mul_f32 v[112:113], v[112:113], v[120:121]
	v_pk_mul_f32 v[114:115], v[114:115], v[122:123]
	v_cvt_pk_bf16_f32 v124, v116, v117
	v_cvt_pk_bf16_f32 v125, v118, v119
	v_cvt_pk_bf16_f32 v126, v112, v113
	v_cvt_pk_bf16_f32 v127, v114, v115
	v_mov_b32_e32 v146, v147
	global_store_dwordx4 v146, v[124:127], s[96:97]
	v_lshlrev_b32_e32 v158, 16, v220
	v_and_b32_e32 v159, 0xffff0000, v220
	v_lshlrev_b32_e32 v160, 16, v221
	v_and_b32_e32 v161, 0xffff0000, v221
	v_lshlrev_b32_e32 v216, 16, v222
	v_and_b32_e32 v217, 0xffff0000, v222
	v_lshlrev_b32_e32 v218, 16, v223
	v_and_b32_e32 v219, 0xffff0000, v223
	v_pk_mul_f32 v[108:109], v[108:109], v[158:159]
	v_pk_mul_f32 v[110:111], v[110:111], v[160:161]
	v_pk_mul_f32 v[104:105], v[104:105], v[216:217]
	v_pk_mul_f32 v[106:107], v[106:107], v[218:219]
	v_pk_mul_f32 v[100:101], v[100:101], v[108:109]
	v_pk_mul_f32 v[102:103], v[102:103], v[110:111]
	v_pk_mul_f32 v[96:97], v[96:97], v[104:105]
	v_pk_mul_f32 v[98:99], v[98:99], v[106:107]
	v_cvt_pk_bf16_f32 v108, v100, v101
	v_cvt_pk_bf16_f32 v109, v102, v103
	v_cvt_pk_bf16_f32 v110, v96, v97
	v_cvt_pk_bf16_f32 v111, v98, v99
	v_add_u32_e32 v146, 0x10000, v147
	global_store_dwordx4 v146, v[108:111], s[96:97]
	v_lshlrev_b32_e32 v158, 16, v224
	v_and_b32_e32 v159, 0xffff0000, v224
	v_lshlrev_b32_e32 v160, 16, v225
	v_and_b32_e32 v161, 0xffff0000, v225
	v_lshlrev_b32_e32 v216, 16, v226
	v_and_b32_e32 v217, 0xffff0000, v226
	v_lshlrev_b32_e32 v218, 16, v227
	v_and_b32_e32 v219, 0xffff0000, v227
	v_pk_mul_f32 v[92:93], v[92:93], v[158:159]
	v_pk_mul_f32 v[94:95], v[94:95], v[160:161]
	v_pk_mul_f32 v[88:89], v[88:89], v[216:217]
	v_pk_mul_f32 v[90:91], v[90:91], v[218:219]
	v_pk_mul_f32 v[84:85], v[84:85], v[92:93]
	v_pk_mul_f32 v[86:87], v[86:87], v[94:95]
	v_pk_mul_f32 v[80:81], v[80:81], v[88:89]
	v_pk_mul_f32 v[82:83], v[82:83], v[90:91]
	v_cvt_pk_bf16_f32 v92, v84, v85
	v_cvt_pk_bf16_f32 v93, v86, v87
	v_cvt_pk_bf16_f32 v94, v80, v81
	v_cvt_pk_bf16_f32 v95, v82, v83
	v_add_u32_e32 v146, 0x20000, v147
	global_store_dwordx4 v146, v[92:95], s[96:97]
	v_lshlrev_b32_e32 v158, 16, v228
	v_and_b32_e32 v159, 0xffff0000, v228
	v_lshlrev_b32_e32 v160, 16, v229
	v_and_b32_e32 v161, 0xffff0000, v229
	v_lshlrev_b32_e32 v216, 16, v230
	v_and_b32_e32 v217, 0xffff0000, v230
	v_lshlrev_b32_e32 v218, 16, v231
	v_and_b32_e32 v219, 0xffff0000, v231
	v_pk_mul_f32 v[76:77], v[76:77], v[158:159]
	v_pk_mul_f32 v[78:79], v[78:79], v[160:161]
	v_pk_mul_f32 v[72:73], v[72:73], v[216:217]
	v_pk_mul_f32 v[74:75], v[74:75], v[218:219]
	v_pk_mul_f32 v[68:69], v[68:69], v[76:77]
	v_pk_mul_f32 v[70:71], v[70:71], v[78:79]
	v_pk_mul_f32 v[64:65], v[64:65], v[72:73]
	v_pk_mul_f32 v[66:67], v[66:67], v[74:75]
	v_cvt_pk_bf16_f32 v76, v68, v69
	v_cvt_pk_bf16_f32 v77, v70, v71
	v_cvt_pk_bf16_f32 v78, v64, v65
	v_cvt_pk_bf16_f32 v79, v66, v67
	v_add_u32_e32 v146, 0x30000, v147
	global_store_dwordx4 v146, v[76:79], s[96:97]
	v_lshlrev_b32_e32 v158, 16, v232
	v_and_b32_e32 v159, 0xffff0000, v232
	v_lshlrev_b32_e32 v160, 16, v233
	v_and_b32_e32 v161, 0xffff0000, v233
	v_lshlrev_b32_e32 v216, 16, v234
	v_and_b32_e32 v217, 0xffff0000, v234
	v_lshlrev_b32_e32 v218, 16, v235
	v_and_b32_e32 v219, 0xffff0000, v235
	v_pk_mul_f32 v[60:61], v[60:61], v[158:159]
	v_pk_mul_f32 v[62:63], v[62:63], v[160:161]
	v_pk_mul_f32 v[56:57], v[56:57], v[216:217]
	v_pk_mul_f32 v[58:59], v[58:59], v[218:219]
	v_pk_mul_f32 v[52:53], v[52:53], v[60:61]
	v_pk_mul_f32 v[54:55], v[54:55], v[62:63]
	v_pk_mul_f32 v[48:49], v[48:49], v[56:57]
	v_pk_mul_f32 v[50:51], v[50:51], v[58:59]
	v_cvt_pk_bf16_f32 v60, v52, v53
	v_cvt_pk_bf16_f32 v61, v54, v55
	v_cvt_pk_bf16_f32 v62, v48, v49
	v_cvt_pk_bf16_f32 v63, v50, v51
	v_add_u32_e32 v146, 0x80000, v147
	global_store_dwordx4 v146, v[60:63], s[96:97]
	v_lshlrev_b32_e32 v158, 16, v236
	v_and_b32_e32 v159, 0xffff0000, v236
	v_lshlrev_b32_e32 v160, 16, v237
	v_and_b32_e32 v161, 0xffff0000, v237
	v_lshlrev_b32_e32 v216, 16, v238
	v_and_b32_e32 v217, 0xffff0000, v238
	v_lshlrev_b32_e32 v218, 16, v239
	v_and_b32_e32 v219, 0xffff0000, v239
	v_pk_mul_f32 v[44:45], v[44:45], v[158:159]
	v_pk_mul_f32 v[46:47], v[46:47], v[160:161]
	v_pk_mul_f32 v[40:41], v[40:41], v[216:217]
	v_pk_mul_f32 v[42:43], v[42:43], v[218:219]
	v_pk_mul_f32 v[36:37], v[36:37], v[44:45]
	v_pk_mul_f32 v[38:39], v[38:39], v[46:47]
	v_pk_mul_f32 v[32:33], v[32:33], v[40:41]
	v_pk_mul_f32 v[34:35], v[34:35], v[42:43]
	v_cvt_pk_bf16_f32 v44, v36, v37
	v_cvt_pk_bf16_f32 v45, v38, v39
	v_cvt_pk_bf16_f32 v46, v32, v33
	v_cvt_pk_bf16_f32 v47, v34, v35
	v_add_u32_e32 v146, 0x90000, v147
	global_store_dwordx4 v146, v[44:47], s[96:97]
	v_lshlrev_b32_e32 v158, 16, v240
	v_and_b32_e32 v159, 0xffff0000, v240
	v_lshlrev_b32_e32 v160, 16, v241
	v_and_b32_e32 v161, 0xffff0000, v241
	v_lshlrev_b32_e32 v216, 16, v242
	v_and_b32_e32 v217, 0xffff0000, v242
	v_lshlrev_b32_e32 v218, 16, v243
	v_and_b32_e32 v219, 0xffff0000, v243
	v_pk_mul_f32 v[28:29], v[28:29], v[158:159]
	v_pk_mul_f32 v[30:31], v[30:31], v[160:161]
	v_pk_mul_f32 v[24:25], v[24:25], v[216:217]
	v_pk_mul_f32 v[26:27], v[26:27], v[218:219]
	v_pk_mul_f32 v[20:21], v[20:21], v[28:29]
	v_pk_mul_f32 v[22:23], v[22:23], v[30:31]
	v_pk_mul_f32 v[16:17], v[16:17], v[24:25]
	v_pk_mul_f32 v[18:19], v[18:19], v[26:27]
	v_cvt_pk_bf16_f32 v28, v20, v21
	v_cvt_pk_bf16_f32 v29, v22, v23
	v_cvt_pk_bf16_f32 v30, v16, v17
	v_cvt_pk_bf16_f32 v31, v18, v19
	v_add_u32_e32 v146, 0xa0000, v147
	global_store_dwordx4 v146, v[28:31], s[96:97]
	v_lshlrev_b32_e32 v158, 16, v244
	v_and_b32_e32 v159, 0xffff0000, v244
	v_lshlrev_b32_e32 v160, 16, v245
	v_and_b32_e32 v161, 0xffff0000, v245
	v_lshlrev_b32_e32 v216, 16, v246
	v_and_b32_e32 v217, 0xffff0000, v246
	v_lshlrev_b32_e32 v218, 16, v247
	v_and_b32_e32 v219, 0xffff0000, v247
	v_pk_mul_f32 v[12:13], v[12:13], v[158:159]
	v_pk_mul_f32 v[14:15], v[14:15], v[160:161]
	v_pk_mul_f32 v[8:9], v[8:9], v[216:217]
	v_pk_mul_f32 v[10:11], v[10:11], v[218:219]
	v_pk_mul_f32 v[4:5], v[4:5], v[12:13]
	v_pk_mul_f32 v[6:7], v[6:7], v[14:15]
	v_pk_mul_f32 v[0:1], v[0:1], v[8:9]
	v_pk_mul_f32 v[2:3], v[2:3], v[10:11]
	v_cvt_pk_bf16_f32 v12, v4, v5
	v_cvt_pk_bf16_f32 v13, v6, v7
	v_cvt_pk_bf16_f32 v14, v0, v1
	v_cvt_pk_bf16_f32 v15, v2, v3
	v_add_u32_e32 v146, 0xb0000, v147
	global_store_dwordx4 v146, v[12:15], s[96:97]
	s_mov_b64 s[20:21], -1
	s_andn2_b64 vcc, exec, s[38:39]
	s_cbranch_vccnz .LBB0_605
	s_andn2_b64 vcc, exec, s[0:1]
	s_cbranch_vccnz .LBB0_604
	s_barrier
	s_branch .LBB0_604
